# 64-bit accumulator clearing in GEMM1/GEMM3 unit headers; MoBA tile loop requests its first 8 K fragments before the staging writes
# speedup vs baseline: 1.0019x; 1.0019x over previous
.Lord1_d:
.LBB0_222:
	s_ashr_i32 s17, s16, 31
	s_lshl_b64 s[18:19], s[16:17], 20
	s_add_u32 s18, s64, s18
	s_addc_u32 s19, s65, s19
	s_and_b64 s[20:21], s[4:5], exec
	s_cselect_b32 s17, s19, s7
	s_cselect_b32 s59, s18, s6
	s_ashr_i32 s15, s14, 31
	s_lshl_b64 s[20:21], s[14:15], 20
	s_add_u32 s20, s68, s20
	s_addc_u32 s21, s69, s21
	s_and_b64 s[28:29], s[4:5], exec
	s_cselect_b32 s15, s21, s27
	s_cselect_b32 s90, s20, s26
	s_add_u32 s6, s6, 0x80080
	s_addc_u32 s7, s7, 0
	s_add_u32 s91, s26, 0x100
	v_mov_b64_e32 v[0:1], 0
	v_mov_b64_e32 v[2:3], 0
	v_mov_b64_e32 v[4:5], 0
	v_mov_b64_e32 v[6:7], 0
	v_mov_b64_e32 v[8:9], 0
	v_mov_b64_e32 v[10:11], 0
	v_mov_b64_e32 v[12:13], 0
	v_mov_b64_e32 v[14:15], 0
	v_mov_b64_e32 v[16:17], 0
	v_mov_b64_e32 v[18:19], 0
	v_mov_b64_e32 v[20:21], 0
	v_mov_b64_e32 v[22:23], 0
	v_mov_b64_e32 v[24:25], 0
	v_mov_b64_e32 v[26:27], 0
	v_mov_b64_e32 v[28:29], 0
	v_mov_b64_e32 v[30:31], 0
	v_mov_b64_e32 v[32:33], 0
	v_mov_b64_e32 v[34:35], 0
	v_mov_b64_e32 v[36:37], 0
	v_mov_b64_e32 v[38:39], 0
	v_mov_b64_e32 v[40:41], 0
	v_mov_b64_e32 v[42:43], 0
	v_mov_b64_e32 v[44:45], 0
	v_mov_b64_e32 v[46:47], 0
	v_mov_b64_e32 v[48:49], 0
	v_mov_b64_e32 v[50:51], 0
	v_mov_b64_e32 v[52:53], 0
	v_mov_b64_e32 v[54:55], 0
	v_mov_b64_e32 v[56:57], 0
	v_mov_b64_e32 v[58:59], 0
	v_mov_b64_e32 v[60:61], 0
	v_mov_b64_e32 v[62:63], 0
	v_mov_b64_e32 v[64:65], 0
	v_mov_b64_e32 v[66:67], 0
	v_mov_b64_e32 v[68:69], 0
	v_mov_b64_e32 v[70:71], 0
	v_mov_b64_e32 v[72:73], 0
	v_mov_b64_e32 v[74:75], 0
	v_mov_b64_e32 v[76:77], 0
	v_mov_b64_e32 v[78:79], 0
	v_mov_b64_e32 v[80:81], 0
	v_mov_b64_e32 v[82:83], 0
	v_mov_b64_e32 v[84:85], 0
	v_mov_b64_e32 v[86:87], 0
	v_mov_b64_e32 v[88:89], 0
	v_mov_b64_e32 v[90:91], 0
	v_mov_b64_e32 v[92:93], 0
	v_mov_b64_e32 v[94:95], 0
	v_mov_b64_e32 v[96:97], 0
	v_mov_b64_e32 v[98:99], 0
	v_mov_b64_e32 v[100:101], 0
	v_mov_b64_e32 v[102:103], 0
	v_mov_b64_e32 v[104:105], 0
	v_mov_b64_e32 v[106:107], 0
	v_mov_b64_e32 v[108:109], 0
	v_mov_b64_e32 v[110:111], 0
	v_mov_b64_e32 v[112:113], 0
	v_mov_b64_e32 v[114:115], 0
	v_mov_b64_e32 v[116:117], 0
	v_mov_b64_e32 v[118:119], 0
	v_mov_b64_e32 v[120:121], 0
	v_mov_b64_e32 v[122:123], 0
	v_mov_b64_e32 v[124:125], 0
	v_mov_b64_e32 v[126:127], 0
	s_addc_u32 s94, s27, 0
	s_mov_b32 s95, -2



.Lmb_loop:
	ds_read_b128 v[204:207], v128 offset:0
	ds_read_b128 v[208:211], v128 offset:64
	ds_read_b128 v[212:215], v128 offset:128
	ds_read_b128 v[216:219], v128 offset:192
	ds_read_b128 v[240:243], v128 offset:4352
	ds_read_b128 v[244:247], v128 offset:4416
	ds_read_b128 v[248:251], v128 offset:4480
	ds_read_b128 v[252:255], v128 offset:4544
	s_add_u32 s30, s23, 1
	s_cmp_ge_u32 s30, s22
	s_cbranch_scc1 .Lmb_nostage
	s_waitcnt vmcnt(0)
	ds_write_b128 v130, v[168:171]
	ds_write_b128 v130, v[172:175] offset:8704
	ds_write_b128 v131, v[176:179]
	ds_write_b128 v131, v[180:183] offset:9216
	s_add_u32 s30, s23, 2
	s_cmp_ge_u32 s30, s22
	s_cbranch_scc1 .Lmb_nostage
	s_lshl_b32 s33, s15, 2
	s_add_u32 s33, s33, s30
	s_sub_u32 s31, s30, 4
	s_cmp_lt_u32 s30, 4
	s_cselect_b32 s31, s33, s31
	s_lshl_b32 s33, s31, 15
	s_add_u32 s33, s33, 0x800000
	s_add_u32 s26, s8, s33
	s_addc_u32 s27, s9, 0
	global_load_dwordx4 v[168:171], v132, s[26:27]
	global_load_dwordx4 v[172:175], v133, s[26:27]
	s_add_u32 s26, s26, 0x800000
	s_addc_u32 s27, s27, 0
	global_load_dwordx4 v[176:179], v132, s[26:27]
	global_load_dwordx4 v[180:183], v133, s[26:27]

.Lmb_S:
	v_xor_b32_e32 v184, 0x80000000, v146
	v_xor_b32_e32 v185, 0x80000000, v146
	v_xor_b32_e32 v186, 0x80000000, v146
	v_xor_b32_e32 v187, 0x80000000, v146
	v_xor_b32_e32 v188, 0x80000000, v147
	v_xor_b32_e32 v189, 0x80000000, v147
	v_xor_b32_e32 v190, 0x80000000, v147
	v_xor_b32_e32 v191, 0x80000000, v147
	s_waitcnt lgkmcnt(7)
	v_mfma_f32_16x16x32_bf16 v[96:99], v[204:207], v[64:67], v[184:187]
	v_mfma_f32_16x16x32_bf16 v[112:115], v[204:207], v[80:83], v[188:191]
	ds_read_b128 v[204:207], v128 offset:8704
	s_waitcnt lgkmcnt(7)
	v_mfma_f32_16x16x32_bf16 v[96:99], v[208:211], v[68:71], v[96:99]
	v_mfma_f32_16x16x32_bf16 v[112:115], v[208:211], v[84:87], v[112:115]
	ds_read_b128 v[208:211], v128 offset:8768
	s_waitcnt lgkmcnt(7)
	v_mfma_f32_16x16x32_bf16 v[96:99], v[212:215], v[72:75], v[96:99]
	v_mfma_f32_16x16x32_bf16 v[112:115], v[212:215], v[88:91], v[112:115]
	ds_read_b128 v[212:215], v128 offset:8832
	s_waitcnt lgkmcnt(7)
	v_mfma_f32_16x16x32_bf16 v[96:99], v[216:219], v[76:79], v[96:99]
	v_mfma_f32_16x16x32_bf16 v[112:115], v[216:219], v[92:95], v[112:115]
	ds_read_b128 v[216:219], v128 offset:8896
	s_waitcnt lgkmcnt(7)
	v_mfma_f32_16x16x32_bf16 v[100:103], v[240:243], v[64:67], v[184:187]
	v_mfma_f32_16x16x32_bf16 v[116:119], v[240:243], v[80:83], v[188:191]
	ds_read_b128 v[240:243], v128 offset:13056
	s_waitcnt lgkmcnt(7)
	v_mfma_f32_16x16x32_bf16 v[100:103], v[244:247], v[68:71], v[100:103]
	v_mfma_f32_16x16x32_bf16 v[116:119], v[244:247], v[84:87], v[116:119]
	ds_read_b128 v[244:247], v128 offset:13120
	s_waitcnt lgkmcnt(7)
	v_mfma_f32_16x16x32_bf16 v[100:103], v[248:251], v[72:75], v[100:103]
	v_mfma_f32_16x16x32_bf16 v[116:119], v[248:251], v[88:91], v[116:119]
	ds_read_b128 v[248:251], v128 offset:13184
	s_waitcnt lgkmcnt(7)
	v_mfma_f32_16x16x32_bf16 v[100:103], v[252:255], v[76:79], v[100:103]
	v_mfma_f32_16x16x32_bf16 v[116:119], v[252:255], v[92:95], v[116:119]
	ds_read_b128 v[252:255], v128 offset:13248
	s_waitcnt lgkmcnt(7)
	v_mfma_f32_16x16x32_bf16 v[104:107], v[204:207], v[64:67], v[184:187]
	v_mfma_f32_16x16x32_bf16 v[120:123], v[204:207], v[80:83], v[188:191]
	s_waitcnt lgkmcnt(6)
	v_mfma_f32_16x16x32_bf16 v[104:107], v[208:211], v[68:71], v[104:107]
	v_mfma_f32_16x16x32_bf16 v[120:123], v[208:211], v[84:87], v[120:123]
	s_waitcnt lgkmcnt(5)
	v_mfma_f32_16x16x32_bf16 v[104:107], v[212:215], v[72:75], v[104:107]
	v_mfma_f32_16x16x32_bf16 v[120:123], v[212:215], v[88:91], v[120:123]
	s_waitcnt lgkmcnt(4)
	v_mfma_f32_16x16x32_bf16 v[104:107], v[216:219], v[76:79], v[104:107]
	v_mfma_f32_16x16x32_bf16 v[120:123], v[216:219], v[92:95], v[120:123]
	s_waitcnt lgkmcnt(3)
	v_mfma_f32_16x16x32_bf16 v[108:111], v[240:243], v[64:67], v[184:187]
	v_mfma_f32_16x16x32_bf16 v[124:127], v[240:243], v[80:83], v[188:191]
	s_waitcnt lgkmcnt(2)
	v_mfma_f32_16x16x32_bf16 v[108:111], v[244:247], v[68:71], v[108:111]
	v_mfma_f32_16x16x32_bf16 v[124:127], v[244:247], v[84:87], v[124:127]
	s_waitcnt lgkmcnt(1)
	v_mfma_f32_16x16x32_bf16 v[108:111], v[248:251], v[72:75], v[108:111]
	v_mfma_f32_16x16x32_bf16 v[124:127], v[248:251], v[88:91], v[124:127]
	s_waitcnt lgkmcnt(0)
	v_mfma_f32_16x16x32_bf16 v[108:111], v[252:255], v[76:79], v[108:111]
	v_mfma_f32_16x16x32_bf16 v[124:127], v[252:255], v[92:95], v[124:127]
	ds_read_b64_tr_b16 v[204:205], v129 offset:0
	ds_read_b64_tr_b16 v[206:207], v129 offset:4608
	ds_read_b64_tr_b16 v[208:209], v129 offset:32
	ds_read_b64_tr_b16 v[210:211], v129 offset:4640
	ds_read_b64_tr_b16 v[212:213], v129 offset:64
	ds_read_b64_tr_b16 v[214:215], v129 offset:4672
	ds_read_b64_tr_b16 v[216:217], v129 offset:96
	ds_read_b64_tr_b16 v[218:219], v129 offset:4704
	ds_read_b64_tr_b16 v[240:241], v129 offset:128
	ds_read_b64_tr_b16 v[242:243], v129 offset:4736
	ds_read_b64_tr_b16 v[244:245], v129 offset:160
	ds_read_b64_tr_b16 v[246:247], v129 offset:4768
	s_cmp_ge_u32 s23, 4
	s_cbranch_scc1 .Lmb_nomask
	v_cmp_le_i32_e64 s[56:57], 0, v138
	v_cmp_le_i32_e64 s[58:59], 1, v138
	v_cmp_le_i32_e64 s[64:65], 2, v138
	v_cmp_le_i32_e64 s[68:69], 3, v138
	v_cndmask_b32_e64 v96, v134, v96, s[56:57]
	v_cndmask_b32_e64 v97, v134, v97, s[58:59]
	v_cndmask_b32_e64 v98, v134, v98, s[64:65]
	v_cndmask_b32_e64 v99, v134, v99, s[68:69]
	v_cmp_le_i32_e64 s[56:57], 16, v138
	v_cmp_le_i32_e64 s[58:59], 17, v138
	v_cmp_le_i32_e64 s[64:65], 18, v138
	v_cmp_le_i32_e64 s[68:69], 19, v138
	v_cndmask_b32_e64 v100, v134, v100, s[56:57]
	v_cndmask_b32_e64 v101, v134, v101, s[58:59]
	v_cndmask_b32_e64 v102, v134, v102, s[64:65]
	v_cndmask_b32_e64 v103, v134, v103, s[68:69]
	v_cmp_le_i32_e64 s[56:57], 32, v138
	v_cmp_le_i32_e64 s[58:59], 33, v138
	v_cmp_le_i32_e64 s[64:65], 34, v138
	v_cmp_le_i32_e64 s[68:69], 35, v138
	v_cndmask_b32_e64 v104, v134, v104, s[56:57]
	v_cndmask_b32_e64 v105, v134, v105, s[58:59]
	v_cndmask_b32_e64 v106, v134, v106, s[64:65]
	v_cndmask_b32_e64 v107, v134, v107, s[68:69]
	v_cmp_le_i32_e64 s[56:57], 48, v138
	v_cmp_le_i32_e64 s[58:59], 49, v138
	v_cmp_le_i32_e64 s[64:65], 50, v138
	v_cmp_le_i32_e64 s[68:69], 51, v138
	v_cndmask_b32_e64 v108, v134, v108, s[56:57]
	v_cndmask_b32_e64 v109, v134, v109, s[58:59]
	v_cndmask_b32_e64 v110, v134, v110, s[64:65]
	v_cndmask_b32_e64 v111, v134, v111, s[68:69]
	v_cmp_le_i32_e64 s[56:57], 0, v139
	v_cmp_le_i32_e64 s[58:59], 1, v139
	v_cmp_le_i32_e64 s[64:65], 2, v139
	v_cmp_le_i32_e64 s[68:69], 3, v139
	v_cndmask_b32_e64 v112, v134, v112, s[56:57]
	v_cndmask_b32_e64 v113, v134, v113, s[58:59]
	v_cndmask_b32_e64 v114, v134, v114, s[64:65]
	v_cndmask_b32_e64 v115, v134, v115, s[68:69]
	v_cmp_le_i32_e64 s[56:57], 16, v139
	v_cmp_le_i32_e64 s[58:59], 17, v139
	v_cmp_le_i32_e64 s[64:65], 18, v139
	v_cmp_le_i32_e64 s[68:69], 19, v139
	v_cndmask_b32_e64 v116, v134, v116, s[56:57]
	v_cndmask_b32_e64 v117, v134, v117, s[58:59]
	v_cndmask_b32_e64 v118, v134, v118, s[64:65]
	v_cndmask_b32_e64 v119, v134, v119, s[68:69]
	v_cmp_le_i32_e64 s[56:57], 32, v139
	v_cmp_le_i32_e64 s[58:59], 33, v139
	v_cmp_le_i32_e64 s[64:65], 34, v139
	v_cmp_le_i32_e64 s[68:69], 35, v139
	v_cndmask_b32_e64 v120, v134, v120, s[56:57]
	v_cndmask_b32_e64 v121, v134, v121, s[58:59]
	v_cndmask_b32_e64 v122, v134, v122, s[64:65]
	v_cndmask_b32_e64 v123, v134, v123, s[68:69]
	v_cmp_le_i32_e64 s[56:57], 48, v139
	v_cmp_le_i32_e64 s[58:59], 49, v139
	v_cmp_le_i32_e64 s[64:65], 50, v139
	v_cmp_le_i32_e64 s[68:69], 51, v139
	v_cndmask_b32_e64 v124, v134, v124, s[56:57]
	v_cndmask_b32_e64 v125, v134, v125, s[58:59]
	v_cndmask_b32_e64 v126, v134, v126, s[64:65]
	v_cndmask_b32_e64 v127, v134, v127, s[68:69]

.LBB0_866:
	s_ashr_i32 s19, s18, 31
	s_lshl_b64 s[20:21], s[18:19], 20
	s_add_u32 s20, s52, s20
	s_addc_u32 s21, s53, s21
	s_and_b64 s[22:23], s[4:5], exec
	s_cselect_b32 s19, s21, s25
	s_cselect_b32 s44, s20, s24
	s_ashr_i32 s17, s16, 31
	s_lshl_b64 s[22:23], s[16:17], 20
	s_add_u32 s22, s40, s22
	s_addc_u32 s23, s41, s23
	s_and_b64 s[28:29], s[4:5], exec
	s_cselect_b32 s17, s23, s27
	s_cselect_b32 s45, s22, s26
	s_add_u32 s24, s24, 0x80080
	s_addc_u32 s25, s25, 0
	s_add_u32 s46, s26, 0x100
	v_mov_b64_e32 v[0:1], 0
	v_mov_b64_e32 v[2:3], 0
	v_mov_b64_e32 v[4:5], 0
	v_mov_b64_e32 v[6:7], 0
	v_mov_b64_e32 v[8:9], 0
	v_mov_b64_e32 v[10:11], 0
	v_mov_b64_e32 v[12:13], 0
	v_mov_b64_e32 v[14:15], 0
	v_mov_b64_e32 v[16:17], 0
	v_mov_b64_e32 v[18:19], 0
	v_mov_b64_e32 v[20:21], 0
	v_mov_b64_e32 v[22:23], 0
	v_mov_b64_e32 v[24:25], 0
	v_mov_b64_e32 v[26:27], 0
	v_mov_b64_e32 v[28:29], 0
	v_mov_b64_e32 v[30:31], 0
	v_mov_b64_e32 v[32:33], 0
	v_mov_b64_e32 v[34:35], 0
	v_mov_b64_e32 v[36:37], 0
	v_mov_b64_e32 v[38:39], 0
	v_mov_b64_e32 v[40:41], 0
	v_mov_b64_e32 v[42:43], 0
	v_mov_b64_e32 v[44:45], 0
	v_mov_b64_e32 v[46:47], 0
	v_mov_b64_e32 v[48:49], 0
	v_mov_b64_e32 v[50:51], 0
	v_mov_b64_e32 v[52:53], 0
	v_mov_b64_e32 v[54:55], 0
	v_mov_b64_e32 v[56:57], 0
	v_mov_b64_e32 v[58:59], 0
	v_mov_b64_e32 v[60:61], 0
	v_mov_b64_e32 v[62:63], 0
	v_mov_b64_e32 v[64:65], 0
	v_mov_b64_e32 v[66:67], 0
	v_mov_b64_e32 v[68:69], 0
	v_mov_b64_e32 v[70:71], 0
	v_mov_b64_e32 v[72:73], 0
	v_mov_b64_e32 v[74:75], 0
	v_mov_b64_e32 v[76:77], 0
	v_mov_b64_e32 v[78:79], 0
	v_mov_b64_e32 v[80:81], 0
	v_mov_b64_e32 v[82:83], 0
	v_mov_b64_e32 v[84:85], 0
	v_mov_b64_e32 v[86:87], 0
	v_mov_b64_e32 v[88:89], 0
	v_mov_b64_e32 v[90:91], 0
	v_mov_b64_e32 v[92:93], 0
	v_mov_b64_e32 v[94:95], 0
	v_mov_b64_e32 v[96:97], 0
	v_mov_b64_e32 v[98:99], 0
	v_mov_b64_e32 v[100:101], 0
	v_mov_b64_e32 v[102:103], 0
	v_mov_b64_e32 v[104:105], 0
	v_mov_b64_e32 v[106:107], 0
	v_mov_b64_e32 v[108:109], 0
	v_mov_b64_e32 v[110:111], 0
	v_mov_b64_e32 v[112:113], 0
	v_mov_b64_e32 v[114:115], 0
	v_mov_b64_e32 v[116:117], 0
	v_mov_b64_e32 v[118:119], 0
	v_mov_b64_e32 v[120:121], 0
	v_mov_b64_e32 v[122:123], 0
	v_mov_b64_e32 v[124:125], 0
	v_mov_b64_e32 v[126:127], 0
	s_addc_u32 s47, s27, 0
	s_mov_b32 s48, -2


	s_waitcnt lgkmcnt(0)


